# v19 + static priority raise for waves 0-3 during attention
# baseline (speedup 1.0000x reference)
; #define LAS __attribute__((address_space(3)))
; __device__ __forceinline__ void attn_phase(LAS unsigned char* lds, const bf16_t* Q, const bf16_t* Kb, const bf16_t* VT, const bf16_t* Z, const float* kpart, bf16_t* Y, int G, int bid) {
;     constexpr int KST = 272, VSTR = 144, KBUF = 64 * KST, VBUF = 128 * VSTR;
;     const int tid = threadIdx.x, wid = __builtin_amdgcn_readfirstlane(tid >> 6), lane = tid & 63, qr = lane & 31, hh = lane >> 5;
;     const float NEG = -__builtin_inff();
;     for (int pair = bid; pair < 256; pair += G) {
;         const int bh = pair >> 2, jp = pair & 3, b = bh >> 4, h = bh & 15;
;         for (int half = 0; half < 2; ++half) {
;             const int own = half == 0 ? 7 - jp : jp;
;             const int q0 = own * 256 + wid * 32;
;             const size_t qoff = (size_t)(b * SEQ + q0 + qr) * DM + h * 128;
;             bf16x8 Qf[8];
; #pragma unroll
;             for (int ks = 0; ks < 8; ++ks) Qf[ks] = *(const bf16x8*)(Q + qoff + ks * 16 + hh * 8);
;             unsigned selmask = (1u << own) - 1u;
;             if (own > 3) {
;                 f32x16 gacc;
; #pragma unroll
;                 for (int j = 0; j < 16; ++j) gacc[j] = 0.f;
; #pragma unroll
;                 for (int ks = 0; ks < 8; ++ks) {
;                     u32x4 w = (u32x4){0u, 0u, 0u, 0u};
;                     if (qr < 8) {
;                         const float* kp = kpart + ((size_t)((b * 8 + qr) * 2)) * DM + h * 128 + ks * 16 + hh * 8;
;                         const f32x4 a0 = *(const f32x4*)(kp), a1 = *(const f32x4*)(kp + 4), c0 = *(const f32x4*)(kp + DM), c1 = *(const f32x4*)(kp + DM + 4);
;                         w = pack8((a0 + c0) * (1.0f / 256.0f), (a1 + c1) * (1.0f / 256.0f));
;                     }
;                     bf16x8 af; __builtin_memcpy(&af, &w, 16);
;                     gacc = MFMA32(af, Qf[ks], gacc);
;                 }
;                 float gt[8];
; #pragma unroll
;                 for (int j = 0; j < 4; ++j) { const float mine = gacc[j], oth = __shfl_xor(mine, 32); gt[j] = hh == 0 ? mine : oth; gt[4 + j] = hh == 0 ? oth : mine; }
; #pragma unroll
;                 for (int j = 0; j < 8; ++j) if (j >= own) gt[j] = NEG;
;                 selmask = 0u;
; #pragma unroll
;                 for (int r = 0; r < 3; ++r) {
;                     float best = NEG; unsigned bi = 0u;
; #pragma unroll
.LBB0_636:
	s_cmpk_gt_i32 s2, 0xff
	v_readfirstlane_b32 s4, v164
	s_barrier
	s_cbranch_scc1 .LBB0_679
	s_bitcmp0_b32 s4, 8
	s_cbranch_scc0 .Lattn_np
	s_setprio 1
.Lattn_np:
	s_waitcnt vmcnt(5)
	v_lshlrev_b32_e32 v3, 4, v164
	v_and_b32_e32 v153, 31, v164
	v_bfe_u32 v1, v164, 5, 1
	s_waitcnt vmcnt(4)
	v_and_b32_e32 v4, 0xf0, v3
	v_lshlrev_b32_e32 v144, 4, v1
	v_add_u32_e32 v157, 0, v4
	v_and_b32_e32 v4, 0x70, v3
	v_mul_u32_u24_e32 v3, 0x110, v153
	v_lshlrev_b32_e32 v0, 3, v1
	v_mov_b32_e32 v145, 0
	v_cmp_eq_u32_e64 s[6:7], 0, v1
	v_add3_u32 v161, 0, v3, v144
	v_lshlrev_b32_e32 v148, 2, v1
	v_lshlrev_b32_e32 v1, 7, v153
	s_add_u32 s28, s40, 0xc000000
	v_sub_u32_e32 v163, v161, v1
	v_mov_b32_e32 v5, v145
	v_lshlrev_b32_e32 v1, 8, v164
	s_addc_u32 s29, s41, 0
	s_lshr_b32 s4, s4, 1
	v_add_u32_e32 v159, 0, v4
	v_lshl_add_u64 v[150:151], s[0:1], 0, v[4:5]
	v_and_b32_e32 v4, 0x3f800, v1
	v_add_u32_e32 v1, 0x200, v164
	s_and_b32 s69, s4, 0x7fffffe0
	v_lshlrev_b32_e32 v2, 3, v164
	v_lshlrev_b32_e32 v3, 8, v1
	v_and_b32_e32 v2, 0x78, v2
	v_lshrrev_b32_e32 v165, 4, v1
	v_and_b32_e32 v6, 0x7f800, v3
	v_lshrrev_b32_e32 v3, 3, v164
	v_lshrrev_b32_e32 v1, 3, v1
	s_cmp_lt_u32 s69, 63
	v_lshlrev_b32_e32 v184, 2, v0
	v_mbcnt_lo_u32_b32 v0, -1, 0
	v_lshl_add_u64 v[146:147], s[14:15], 0, v[144:145]
	v_cmp_gt_u32_e64 s[4:5], 8, v153
	v_lshlrev_b32_e32 v155, 1, v153
	s_mov_b32 s31, 0
	v_or_b32_e32 v152, 0x60, v148
	v_mul_u32_u24_e32 v167, 0x110, v214
	v_mul_u32_u24_e32 v169, 0x90, v3
	v_mul_u32_u24_e32 v171, 0x110, v165
	v_mul_u32_u24_e32 v173, 0x90, v1
	v_mov_b32_e32 v149, v145
	v_or_b32_e32 v154, 8, v148
	v_or_b32_e32 v156, 16, v148
	v_or_b32_e32 v158, 24, v148
	v_or_b32_e32 v160, 32, v148
	v_or_b32_e32 v162, 40, v148
	v_or_b32_e32 v166, 48, v148
	v_or_b32_e32 v168, 56, v148
	v_or_b32_e32 v170, 64, v148
	v_or_b32_e32 v172, 0x48, v148
	v_or_b32_e32 v174, 0x50, v148
	v_or_b32_e32 v176, 0x58, v148
	v_or_b32_e32 v178, 0x68, v148
	v_or_b32_e32 v180, 0x70, v148
	v_or_b32_e32 v182, 0x78, v148
	s_cselect_b64 s[36:37], -1, 0
	v_lshlrev_b32_e32 v186, 1, v2
	s_mov_b64 s[44:45], 0x2000
	s_mov_b64 s[50:51], 0x2040
	s_mov_b64 s[56:57], 0x2080
	s_mov_b64 s[58:59], 0x20c0
	s_mov_b64 s[60:61], 0x2100
	s_mov_b64 s[62:63], 0x2140
	s_mov_b64 s[64:65], 0x2180
	s_mov_b64 s[66:67], 0x21c0
	s_mov_b32 s68, 0x3b800000
	s_mov_b32 s72, 0xff800000
	v_lshlrev_b32_e32 v144, 1, v4
	v_lshlrev_b32_e32 v188, 1, v6
	v_mbcnt_hi_u32_b32 v175, -1, v0
	v_mov_b32_e32 v185, v145
	v_mov_b32_e32 v187, v145
	v_mov_b32_e32 v177, 0xff800000
	s_mov_b32 s73, s2
	s_branch .LBB0_639
